# bounded in-flight queues: copy_caches keeps at most ~44 memory operations outstanding, cross-attention V staging waits every 8 LDS writes
# baseline (speedup 1.0000x reference)
.Lcc_no17:
	s_lshl_b32 s13, s10, 11
	s_add_u32 s98, s36, s13
	s_addc_u32 s99, s37, 0
	s_add_u32 s100, s98, 0x12100000
	s_addc_u32 s101, s99, 0
	s_add_u32 s98, s98, 0x10100000
	s_addc_u32 s99, s99, 0
	s_cmp_lt_u32 s10, 0x100
	s_cbranch_scc0 .Lcc_r16
	s_waitcnt vmcnt(33)
	v_lshlrev_b32_e32 v140, 16, v0
	v_and_b32_e32 v141, 0xffff0000, v0
	v_lshlrev_b32_e32 v142, 16, v1
	v_and_b32_e32 v143, 0xffff0000, v1
	v_lshlrev_b32_e32 v144, 16, v2
	v_and_b32_e32 v145, 0xffff0000, v2
	v_lshlrev_b32_e32 v146, 16, v3
	v_and_b32_e32 v147, 0xffff0000, v3
	global_store_dwordx4 v173, v[140:143], s[98:99]
	global_store_dwordx4 v173, v[144:147], s[98:99] offset:16
	s_waitcnt vmcnt(34)
	v_lshlrev_b32_e32 v148, 16, v4
	v_and_b32_e32 v149, 0xffff0000, v4
	v_lshlrev_b32_e32 v150, 16, v5
	v_and_b32_e32 v151, 0xffff0000, v5
	v_lshlrev_b32_e32 v152, 16, v6
	v_and_b32_e32 v153, 0xffff0000, v6
	v_lshlrev_b32_e32 v154, 16, v7
	v_and_b32_e32 v155, 0xffff0000, v7
	global_store_dwordx4 v173, v[148:151], s[100:101]
	global_store_dwordx4 v173, v[152:155], s[100:101] offset:16
	s_add_u32 s98, s98, 0x200000
	s_addc_u32 s99, s99, 0
	s_add_u32 s100, s100, 0x200000
	s_addc_u32 s101, s101, 0
	s_waitcnt vmcnt(35)
	v_lshlrev_b32_e32 v156, 16, v8
	v_and_b32_e32 v157, 0xffff0000, v8
	v_lshlrev_b32_e32 v158, 16, v9
	v_and_b32_e32 v159, 0xffff0000, v9
	v_lshlrev_b32_e32 v160, 16, v10
	v_and_b32_e32 v161, 0xffff0000, v10
	v_lshlrev_b32_e32 v162, 16, v11
	v_and_b32_e32 v163, 0xffff0000, v11
	global_store_dwordx4 v173, v[156:159], s[98:99]
	global_store_dwordx4 v173, v[160:163], s[98:99] offset:16
	s_waitcnt vmcnt(36)
	v_lshlrev_b32_e32 v164, 16, v12
	v_and_b32_e32 v165, 0xffff0000, v12
	v_lshlrev_b32_e32 v166, 16, v13
	v_and_b32_e32 v167, 0xffff0000, v13
	v_lshlrev_b32_e32 v168, 16, v14
	v_and_b32_e32 v169, 0xffff0000, v14
	v_lshlrev_b32_e32 v170, 16, v15
	v_and_b32_e32 v171, 0xffff0000, v15
	global_store_dwordx4 v173, v[164:167], s[100:101]
	global_store_dwordx4 v173, v[168:171], s[100:101] offset:16
	s_add_u32 s98, s98, 0x200000
	s_addc_u32 s99, s99, 0
	s_add_u32 s100, s100, 0x200000
	s_addc_u32 s101, s101, 0
	s_waitcnt vmcnt(37)
	v_lshlrev_b32_e32 v140, 16, v16
	v_and_b32_e32 v141, 0xffff0000, v16
	v_lshlrev_b32_e32 v142, 16, v17
	v_and_b32_e32 v143, 0xffff0000, v17
	v_lshlrev_b32_e32 v144, 16, v18
	v_and_b32_e32 v145, 0xffff0000, v18
	v_lshlrev_b32_e32 v146, 16, v19
	v_and_b32_e32 v147, 0xffff0000, v19
	global_store_dwordx4 v173, v[140:143], s[98:99]
	global_store_dwordx4 v173, v[144:147], s[98:99] offset:16
	s_waitcnt vmcnt(38)
	v_lshlrev_b32_e32 v148, 16, v20
	v_and_b32_e32 v149, 0xffff0000, v20
	v_lshlrev_b32_e32 v150, 16, v21
	v_and_b32_e32 v151, 0xffff0000, v21
	v_lshlrev_b32_e32 v152, 16, v22
	v_and_b32_e32 v153, 0xffff0000, v22
	v_lshlrev_b32_e32 v154, 16, v23
	v_and_b32_e32 v155, 0xffff0000, v23
	global_store_dwordx4 v173, v[148:151], s[100:101]
	global_store_dwordx4 v173, v[152:155], s[100:101] offset:16
	s_add_u32 s98, s98, 0x200000
	s_addc_u32 s99, s99, 0
	s_add_u32 s100, s100, 0x200000
	s_addc_u32 s101, s101, 0
	s_waitcnt vmcnt(39)
	v_lshlrev_b32_e32 v156, 16, v24
	v_and_b32_e32 v157, 0xffff0000, v24
	v_lshlrev_b32_e32 v158, 16, v25
	v_and_b32_e32 v159, 0xffff0000, v25
	v_lshlrev_b32_e32 v160, 16, v26
	v_and_b32_e32 v161, 0xffff0000, v26
	v_lshlrev_b32_e32 v162, 16, v27
	v_and_b32_e32 v163, 0xffff0000, v27
	global_store_dwordx4 v173, v[156:159], s[98:99]
	global_store_dwordx4 v173, v[160:163], s[98:99] offset:16
	s_waitcnt vmcnt(40)
	v_lshlrev_b32_e32 v164, 16, v28
	v_and_b32_e32 v165, 0xffff0000, v28
	v_lshlrev_b32_e32 v166, 16, v29
	v_and_b32_e32 v167, 0xffff0000, v29
	v_lshlrev_b32_e32 v168, 16, v30
	v_and_b32_e32 v169, 0xffff0000, v30
	v_lshlrev_b32_e32 v170, 16, v31
	v_and_b32_e32 v171, 0xffff0000, v31
	global_store_dwordx4 v173, v[164:167], s[100:101]
	global_store_dwordx4 v173, v[168:171], s[100:101] offset:16
	s_add_u32 s98, s98, 0x200000
	s_addc_u32 s99, s99, 0
	s_add_u32 s100, s100, 0x200000
	s_addc_u32 s101, s101, 0
	s_waitcnt vmcnt(40)
	v_lshlrev_b32_e32 v140, 16, v32
	v_and_b32_e32 v141, 0xffff0000, v32
	v_lshlrev_b32_e32 v142, 16, v33
	v_and_b32_e32 v143, 0xffff0000, v33
	v_lshlrev_b32_e32 v144, 16, v34
	v_and_b32_e32 v145, 0xffff0000, v34
	v_lshlrev_b32_e32 v146, 16, v35
	v_and_b32_e32 v147, 0xffff0000, v35
	global_store_dwordx4 v173, v[140:143], s[98:99]
	global_store_dwordx4 v173, v[144:147], s[98:99] offset:16
	s_waitcnt vmcnt(40)
	v_lshlrev_b32_e32 v148, 16, v36
	v_and_b32_e32 v149, 0xffff0000, v36
	v_lshlrev_b32_e32 v150, 16, v37
	v_and_b32_e32 v151, 0xffff0000, v37
	v_lshlrev_b32_e32 v152, 16, v38
	v_and_b32_e32 v153, 0xffff0000, v38
	v_lshlrev_b32_e32 v154, 16, v39
	v_and_b32_e32 v155, 0xffff0000, v39
	global_store_dwordx4 v173, v[148:151], s[100:101]
	global_store_dwordx4 v173, v[152:155], s[100:101] offset:16
	s_add_u32 s98, s98, 0x200000
	s_addc_u32 s99, s99, 0
	s_add_u32 s100, s100, 0x200000
	s_addc_u32 s101, s101, 0
	s_waitcnt vmcnt(40)
	v_lshlrev_b32_e32 v156, 16, v40
	v_and_b32_e32 v157, 0xffff0000, v40
	v_lshlrev_b32_e32 v158, 16, v41
	v_and_b32_e32 v159, 0xffff0000, v41
	v_lshlrev_b32_e32 v160, 16, v42
	v_and_b32_e32 v161, 0xffff0000, v42
	v_lshlrev_b32_e32 v162, 16, v43
	v_and_b32_e32 v163, 0xffff0000, v43
	global_store_dwordx4 v173, v[156:159], s[98:99]
	global_store_dwordx4 v173, v[160:163], s[98:99] offset:16
	s_waitcnt vmcnt(40)
	v_lshlrev_b32_e32 v164, 16, v44
	v_and_b32_e32 v165, 0xffff0000, v44
	v_lshlrev_b32_e32 v166, 16, v45
	v_and_b32_e32 v167, 0xffff0000, v45
	v_lshlrev_b32_e32 v168, 16, v46
	v_and_b32_e32 v169, 0xffff0000, v46
	v_lshlrev_b32_e32 v170, 16, v47
	v_and_b32_e32 v171, 0xffff0000, v47
	global_store_dwordx4 v173, v[164:167], s[100:101]
	global_store_dwordx4 v173, v[168:171], s[100:101] offset:16
	s_add_u32 s98, s98, 0x200000
	s_addc_u32 s99, s99, 0
	s_add_u32 s100, s100, 0x200000
	s_addc_u32 s101, s101, 0
	s_waitcnt vmcnt(40)
	v_lshlrev_b32_e32 v140, 16, v48
	v_and_b32_e32 v141, 0xffff0000, v48
	v_lshlrev_b32_e32 v142, 16, v49
	v_and_b32_e32 v143, 0xffff0000, v49
	v_lshlrev_b32_e32 v144, 16, v50
	v_and_b32_e32 v145, 0xffff0000, v50
	v_lshlrev_b32_e32 v146, 16, v51
	v_and_b32_e32 v147, 0xffff0000, v51
	global_store_dwordx4 v173, v[140:143], s[98:99]
	global_store_dwordx4 v173, v[144:147], s[98:99] offset:16
	s_waitcnt vmcnt(40)
	v_lshlrev_b32_e32 v148, 16, v52
	v_and_b32_e32 v149, 0xffff0000, v52
	v_lshlrev_b32_e32 v150, 16, v53
	v_and_b32_e32 v151, 0xffff0000, v53
	v_lshlrev_b32_e32 v152, 16, v54
	v_and_b32_e32 v153, 0xffff0000, v54
	v_lshlrev_b32_e32 v154, 16, v55
	v_and_b32_e32 v155, 0xffff0000, v55
	global_store_dwordx4 v173, v[148:151], s[100:101]
	global_store_dwordx4 v173, v[152:155], s[100:101] offset:16
	s_add_u32 s98, s98, 0x200000
	s_addc_u32 s99, s99, 0
	s_add_u32 s100, s100, 0x200000
	s_addc_u32 s101, s101, 0
	s_waitcnt vmcnt(40)
	v_lshlrev_b32_e32 v156, 16, v56
	v_and_b32_e32 v157, 0xffff0000, v56
	v_lshlrev_b32_e32 v158, 16, v57
	v_and_b32_e32 v159, 0xffff0000, v57
	v_lshlrev_b32_e32 v160, 16, v58
	v_and_b32_e32 v161, 0xffff0000, v58
	v_lshlrev_b32_e32 v162, 16, v59
	v_and_b32_e32 v163, 0xffff0000, v59
	global_store_dwordx4 v173, v[156:159], s[98:99]
	global_store_dwordx4 v173, v[160:163], s[98:99] offset:16
	s_waitcnt vmcnt(40)
	v_lshlrev_b32_e32 v164, 16, v60
	v_and_b32_e32 v165, 0xffff0000, v60
	v_lshlrev_b32_e32 v166, 16, v61
	v_and_b32_e32 v167, 0xffff0000, v61
	v_lshlrev_b32_e32 v168, 16, v62
	v_and_b32_e32 v169, 0xffff0000, v62
	v_lshlrev_b32_e32 v170, 16, v63
	v_and_b32_e32 v171, 0xffff0000, v63
	global_store_dwordx4 v173, v[164:167], s[100:101]
	global_store_dwordx4 v173, v[168:171], s[100:101] offset:16
	s_add_u32 s98, s98, 0x200000
	s_addc_u32 s99, s99, 0
	s_add_u32 s100, s100, 0x200000
	s_addc_u32 s101, s101, 0
	s_waitcnt vmcnt(40)
	v_lshlrev_b32_e32 v140, 16, v68
	v_and_b32_e32 v141, 0xffff0000, v68
	v_lshlrev_b32_e32 v142, 16, v69
	v_and_b32_e32 v143, 0xffff0000, v69
	v_lshlrev_b32_e32 v144, 16, v70
	v_and_b32_e32 v145, 0xffff0000, v70
	v_lshlrev_b32_e32 v146, 16, v71
	v_and_b32_e32 v147, 0xffff0000, v71
	global_store_dwordx4 v173, v[140:143], s[98:99]
	global_store_dwordx4 v173, v[144:147], s[98:99] offset:16
	s_waitcnt vmcnt(40)
	v_lshlrev_b32_e32 v148, 16, v72
	v_and_b32_e32 v149, 0xffff0000, v72
	v_lshlrev_b32_e32 v150, 16, v73
	v_and_b32_e32 v151, 0xffff0000, v73
	v_lshlrev_b32_e32 v152, 16, v74
	v_and_b32_e32 v153, 0xffff0000, v74
	v_lshlrev_b32_e32 v154, 16, v75
	v_and_b32_e32 v155, 0xffff0000, v75
	global_store_dwordx4 v173, v[148:151], s[100:101]
	global_store_dwordx4 v173, v[152:155], s[100:101] offset:16
	s_add_u32 s98, s98, 0x200000
	s_addc_u32 s99, s99, 0
	s_add_u32 s100, s100, 0x200000
	s_addc_u32 s101, s101, 0
	s_waitcnt vmcnt(40)
	v_lshlrev_b32_e32 v156, 16, v76
	v_and_b32_e32 v157, 0xffff0000, v76
	v_lshlrev_b32_e32 v158, 16, v77
	v_and_b32_e32 v159, 0xffff0000, v77
	v_lshlrev_b32_e32 v160, 16, v78
	v_and_b32_e32 v161, 0xffff0000, v78
	v_lshlrev_b32_e32 v162, 16, v79
	v_and_b32_e32 v163, 0xffff0000, v79
	global_store_dwordx4 v173, v[156:159], s[98:99]
	global_store_dwordx4 v173, v[160:163], s[98:99] offset:16
	s_waitcnt vmcnt(40)
	v_lshlrev_b32_e32 v164, 16, v80
	v_and_b32_e32 v165, 0xffff0000, v80
	v_lshlrev_b32_e32 v166, 16, v81
	v_and_b32_e32 v167, 0xffff0000, v81
	v_lshlrev_b32_e32 v168, 16, v82
	v_and_b32_e32 v169, 0xffff0000, v82
	v_lshlrev_b32_e32 v170, 16, v83
	v_and_b32_e32 v171, 0xffff0000, v83
	global_store_dwordx4 v173, v[164:167], s[100:101]
	global_store_dwordx4 v173, v[168:171], s[100:101] offset:16
	s_add_u32 s98, s98, 0x200000
	s_addc_u32 s99, s99, 0
	s_add_u32 s100, s100, 0x200000
	s_addc_u32 s101, s101, 0
	s_waitcnt vmcnt(40)
	v_lshlrev_b32_e32 v140, 16, v84
	v_and_b32_e32 v141, 0xffff0000, v84
	v_lshlrev_b32_e32 v142, 16, v85
	v_and_b32_e32 v143, 0xffff0000, v85
	v_lshlrev_b32_e32 v144, 16, v86
	v_and_b32_e32 v145, 0xffff0000, v86
	v_lshlrev_b32_e32 v146, 16, v87
	v_and_b32_e32 v147, 0xffff0000, v87
	global_store_dwordx4 v173, v[140:143], s[98:99]
	global_store_dwordx4 v173, v[144:147], s[98:99] offset:16
	s_waitcnt vmcnt(40)
	v_lshlrev_b32_e32 v148, 16, v88
	v_and_b32_e32 v149, 0xffff0000, v88
	v_lshlrev_b32_e32 v150, 16, v89
	v_and_b32_e32 v151, 0xffff0000, v89
	v_lshlrev_b32_e32 v152, 16, v90
	v_and_b32_e32 v153, 0xffff0000, v90
	v_lshlrev_b32_e32 v154, 16, v91
	v_and_b32_e32 v155, 0xffff0000, v91
	global_store_dwordx4 v173, v[148:151], s[100:101]
	global_store_dwordx4 v173, v[152:155], s[100:101] offset:16
	s_add_u32 s98, s98, 0x200000
	s_addc_u32 s99, s99, 0
	s_add_u32 s100, s100, 0x200000
	s_addc_u32 s101, s101, 0
	s_waitcnt vmcnt(40)
	v_lshlrev_b32_e32 v156, 16, v92
	v_and_b32_e32 v157, 0xffff0000, v92
	v_lshlrev_b32_e32 v158, 16, v93
	v_and_b32_e32 v159, 0xffff0000, v93
	v_lshlrev_b32_e32 v160, 16, v94
	v_and_b32_e32 v161, 0xffff0000, v94
	v_lshlrev_b32_e32 v162, 16, v95
	v_and_b32_e32 v163, 0xffff0000, v95
	global_store_dwordx4 v173, v[156:159], s[98:99]
	global_store_dwordx4 v173, v[160:163], s[98:99] offset:16
	s_waitcnt vmcnt(40)
	v_lshlrev_b32_e32 v164, 16, v96
	v_and_b32_e32 v165, 0xffff0000, v96
	v_lshlrev_b32_e32 v166, 16, v97
	v_and_b32_e32 v167, 0xffff0000, v97
	v_lshlrev_b32_e32 v168, 16, v98
	v_and_b32_e32 v169, 0xffff0000, v98
	v_lshlrev_b32_e32 v170, 16, v99
	v_and_b32_e32 v171, 0xffff0000, v99
	global_store_dwordx4 v173, v[164:167], s[100:101]
	global_store_dwordx4 v173, v[168:171], s[100:101] offset:16
	s_add_u32 s98, s98, 0x200000
	s_addc_u32 s99, s99, 0
	s_add_u32 s100, s100, 0x200000
	s_addc_u32 s101, s101, 0
	s_waitcnt vmcnt(40)
	v_lshlrev_b32_e32 v140, 16, v100
	v_and_b32_e32 v141, 0xffff0000, v100
	v_lshlrev_b32_e32 v142, 16, v101
	v_and_b32_e32 v143, 0xffff0000, v101
	v_lshlrev_b32_e32 v144, 16, v102
	v_and_b32_e32 v145, 0xffff0000, v102
	v_lshlrev_b32_e32 v146, 16, v103
	v_and_b32_e32 v147, 0xffff0000, v103
	global_store_dwordx4 v173, v[140:143], s[98:99]
	global_store_dwordx4 v173, v[144:147], s[98:99] offset:16
	s_waitcnt vmcnt(40)
	v_lshlrev_b32_e32 v148, 16, v104
	v_and_b32_e32 v149, 0xffff0000, v104
	v_lshlrev_b32_e32 v150, 16, v105
	v_and_b32_e32 v151, 0xffff0000, v105
	v_lshlrev_b32_e32 v152, 16, v106
	v_and_b32_e32 v153, 0xffff0000, v106
	v_lshlrev_b32_e32 v154, 16, v107
	v_and_b32_e32 v155, 0xffff0000, v107
	global_store_dwordx4 v173, v[148:151], s[100:101]
	global_store_dwordx4 v173, v[152:155], s[100:101] offset:16
	s_add_u32 s98, s98, 0x200000
	s_addc_u32 s99, s99, 0
	s_add_u32 s100, s100, 0x200000
	s_addc_u32 s101, s101, 0
	s_waitcnt vmcnt(40)
	v_lshlrev_b32_e32 v156, 16, v108
	v_and_b32_e32 v157, 0xffff0000, v108
	v_lshlrev_b32_e32 v158, 16, v109
	v_and_b32_e32 v159, 0xffff0000, v109
	v_lshlrev_b32_e32 v160, 16, v110
	v_and_b32_e32 v161, 0xffff0000, v110
	v_lshlrev_b32_e32 v162, 16, v111
	v_and_b32_e32 v163, 0xffff0000, v111
	global_store_dwordx4 v173, v[156:159], s[98:99]
	global_store_dwordx4 v173, v[160:163], s[98:99] offset:16
	s_waitcnt vmcnt(40)
	v_lshlrev_b32_e32 v164, 16, v112
	v_and_b32_e32 v165, 0xffff0000, v112
	v_lshlrev_b32_e32 v166, 16, v113
	v_and_b32_e32 v167, 0xffff0000, v113
	v_lshlrev_b32_e32 v168, 16, v114
	v_and_b32_e32 v169, 0xffff0000, v114
	v_lshlrev_b32_e32 v170, 16, v115
	v_and_b32_e32 v171, 0xffff0000, v115
	global_store_dwordx4 v173, v[164:167], s[100:101]
	global_store_dwordx4 v173, v[168:171], s[100:101] offset:16
	s_add_u32 s98, s98, 0x200000
	s_addc_u32 s99, s99, 0
	s_add_u32 s100, s100, 0x200000
	s_addc_u32 s101, s101, 0
	s_waitcnt vmcnt(40)
	v_lshlrev_b32_e32 v140, 16, v116
	v_and_b32_e32 v141, 0xffff0000, v116
	v_lshlrev_b32_e32 v142, 16, v117
	v_and_b32_e32 v143, 0xffff0000, v117
	v_lshlrev_b32_e32 v144, 16, v118
	v_and_b32_e32 v145, 0xffff0000, v118
	v_lshlrev_b32_e32 v146, 16, v119
	v_and_b32_e32 v147, 0xffff0000, v119
	global_store_dwordx4 v173, v[140:143], s[98:99]
	global_store_dwordx4 v173, v[144:147], s[98:99] offset:16
	s_waitcnt vmcnt(40)
	v_lshlrev_b32_e32 v148, 16, v120
	v_and_b32_e32 v149, 0xffff0000, v120
	v_lshlrev_b32_e32 v150, 16, v121
	v_and_b32_e32 v151, 0xffff0000, v121
	v_lshlrev_b32_e32 v152, 16, v122
	v_and_b32_e32 v153, 0xffff0000, v122
	v_lshlrev_b32_e32 v154, 16, v123
	v_and_b32_e32 v155, 0xffff0000, v123
	global_store_dwordx4 v173, v[148:151], s[100:101]
	global_store_dwordx4 v173, v[152:155], s[100:101] offset:16
	s_add_u32 s98, s98, 0x200000
	s_addc_u32 s99, s99, 0
	s_add_u32 s100, s100, 0x200000
	s_addc_u32 s101, s101, 0
	s_waitcnt vmcnt(40)
	v_lshlrev_b32_e32 v156, 16, v124
	v_and_b32_e32 v157, 0xffff0000, v124
	v_lshlrev_b32_e32 v158, 16, v125
	v_and_b32_e32 v159, 0xffff0000, v125
	v_lshlrev_b32_e32 v160, 16, v126
	v_and_b32_e32 v161, 0xffff0000, v126
	v_lshlrev_b32_e32 v162, 16, v127
	v_and_b32_e32 v163, 0xffff0000, v127
	global_store_dwordx4 v173, v[156:159], s[98:99]
	global_store_dwordx4 v173, v[160:163], s[98:99] offset:16
	s_waitcnt vmcnt(40)
	v_lshlrev_b32_e32 v164, 16, v128
	v_and_b32_e32 v165, 0xffff0000, v128
	v_lshlrev_b32_e32 v166, 16, v129
	v_and_b32_e32 v167, 0xffff0000, v129
	v_lshlrev_b32_e32 v168, 16, v130
	v_and_b32_e32 v169, 0xffff0000, v130
	v_lshlrev_b32_e32 v170, 16, v131
	v_and_b32_e32 v171, 0xffff0000, v131
	global_store_dwordx4 v173, v[164:167], s[100:101]
	global_store_dwordx4 v173, v[168:171], s[100:101] offset:16
	s_lshl_b32 s13, s10, 11
	s_add_u32 s98, s36, s13
	s_addc_u32 s99, s37, 0
	s_add_u32 s100, s98, 0x18a10000
	s_addc_u32 s101, s99, 0
	s_add_u32 s98, s98, 0x18990000
	s_addc_u32 s99, s99, 0
	s_waitcnt vmcnt(0)
	v_lshlrev_b32_e32 v140, 16, v132
	v_and_b32_e32 v141, 0xffff0000, v132
	v_lshlrev_b32_e32 v142, 16, v133
	v_and_b32_e32 v143, 0xffff0000, v133
	v_lshlrev_b32_e32 v144, 16, v134
	v_and_b32_e32 v145, 0xffff0000, v134
	v_lshlrev_b32_e32 v146, 16, v135
	v_and_b32_e32 v147, 0xffff0000, v135
	global_store_dwordx4 v173, v[140:143], s[98:99]
	global_store_dwordx4 v173, v[144:147], s[98:99] offset:16
	v_lshlrev_b32_e32 v148, 16, v136
	v_and_b32_e32 v149, 0xffff0000, v136
	v_lshlrev_b32_e32 v150, 16, v137
	v_and_b32_e32 v151, 0xffff0000, v137
	v_lshlrev_b32_e32 v152, 16, v138
	v_and_b32_e32 v153, 0xffff0000, v138
	v_lshlrev_b32_e32 v154, 16, v139
	v_and_b32_e32 v155, 0xffff0000, v139
	global_store_dwordx4 v173, v[148:151], s[100:101]
	global_store_dwordx4 v173, v[152:155], s[100:101] offset:16
	s_branch .Lcc_done
.Lcc_r16:
	s_waitcnt vmcnt(31)
	v_lshlrev_b32_e32 v156, 16, v0
	v_and_b32_e32 v157, 0xffff0000, v0
	v_lshlrev_b32_e32 v158, 16, v1
	v_and_b32_e32 v159, 0xffff0000, v1
	v_lshlrev_b32_e32 v160, 16, v2
	v_and_b32_e32 v161, 0xffff0000, v2
	v_lshlrev_b32_e32 v162, 16, v3
	v_and_b32_e32 v163, 0xffff0000, v3
	global_store_dwordx4 v173, v[156:159], s[98:99]
	global_store_dwordx4 v173, v[160:163], s[98:99] offset:16
	s_waitcnt vmcnt(32)
	v_lshlrev_b32_e32 v164, 16, v4
	v_and_b32_e32 v165, 0xffff0000, v4
	v_lshlrev_b32_e32 v166, 16, v5
	v_and_b32_e32 v167, 0xffff0000, v5
	v_lshlrev_b32_e32 v168, 16, v6
	v_and_b32_e32 v169, 0xffff0000, v6
	v_lshlrev_b32_e32 v170, 16, v7
	v_and_b32_e32 v171, 0xffff0000, v7
	global_store_dwordx4 v173, v[164:167], s[100:101]
	global_store_dwordx4 v173, v[168:171], s[100:101] offset:16
	s_add_u32 s98, s98, 0x200000
	s_addc_u32 s99, s99, 0
	s_add_u32 s100, s100, 0x200000
	s_addc_u32 s101, s101, 0
	s_waitcnt vmcnt(33)
	v_lshlrev_b32_e32 v140, 16, v8
	v_and_b32_e32 v141, 0xffff0000, v8
	v_lshlrev_b32_e32 v142, 16, v9
	v_and_b32_e32 v143, 0xffff0000, v9
	v_lshlrev_b32_e32 v144, 16, v10
	v_and_b32_e32 v145, 0xffff0000, v10
	v_lshlrev_b32_e32 v146, 16, v11
	v_and_b32_e32 v147, 0xffff0000, v11
	global_store_dwordx4 v173, v[140:143], s[98:99]
	global_store_dwordx4 v173, v[144:147], s[98:99] offset:16
	s_waitcnt vmcnt(34)
	v_lshlrev_b32_e32 v148, 16, v12
	v_and_b32_e32 v149, 0xffff0000, v12
	v_lshlrev_b32_e32 v150, 16, v13
	v_and_b32_e32 v151, 0xffff0000, v13
	v_lshlrev_b32_e32 v152, 16, v14
	v_and_b32_e32 v153, 0xffff0000, v14
	v_lshlrev_b32_e32 v154, 16, v15
	v_and_b32_e32 v155, 0xffff0000, v15
	global_store_dwordx4 v173, v[148:151], s[100:101]
	global_store_dwordx4 v173, v[152:155], s[100:101] offset:16
	s_add_u32 s98, s98, 0x200000
	s_addc_u32 s99, s99, 0
	s_add_u32 s100, s100, 0x200000
	s_addc_u32 s101, s101, 0
	s_waitcnt vmcnt(35)
	v_lshlrev_b32_e32 v156, 16, v16
	v_and_b32_e32 v157, 0xffff0000, v16
	v_lshlrev_b32_e32 v158, 16, v17
	v_and_b32_e32 v159, 0xffff0000, v17
	v_lshlrev_b32_e32 v160, 16, v18
	v_and_b32_e32 v161, 0xffff0000, v18
	v_lshlrev_b32_e32 v162, 16, v19
	v_and_b32_e32 v163, 0xffff0000, v19
	global_store_dwordx4 v173, v[156:159], s[98:99]
	global_store_dwordx4 v173, v[160:163], s[98:99] offset:16
	s_waitcnt vmcnt(36)
	v_lshlrev_b32_e32 v164, 16, v20
	v_and_b32_e32 v165, 0xffff0000, v20
	v_lshlrev_b32_e32 v166, 16, v21
	v_and_b32_e32 v167, 0xffff0000, v21
	v_lshlrev_b32_e32 v168, 16, v22
	v_and_b32_e32 v169, 0xffff0000, v22
	v_lshlrev_b32_e32 v170, 16, v23
	v_and_b32_e32 v171, 0xffff0000, v23
	global_store_dwordx4 v173, v[164:167], s[100:101]
	global_store_dwordx4 v173, v[168:171], s[100:101] offset:16
	s_add_u32 s98, s98, 0x200000
	s_addc_u32 s99, s99, 0
	s_add_u32 s100, s100, 0x200000
	s_addc_u32 s101, s101, 0
	s_waitcnt vmcnt(37)
	v_lshlrev_b32_e32 v140, 16, v24
	v_and_b32_e32 v141, 0xffff0000, v24
	v_lshlrev_b32_e32 v142, 16, v25
	v_and_b32_e32 v143, 0xffff0000, v25
	v_lshlrev_b32_e32 v144, 16, v26
	v_and_b32_e32 v145, 0xffff0000, v26
	v_lshlrev_b32_e32 v146, 16, v27
	v_and_b32_e32 v147, 0xffff0000, v27
	global_store_dwordx4 v173, v[140:143], s[98:99]
	global_store_dwordx4 v173, v[144:147], s[98:99] offset:16
	s_waitcnt vmcnt(38)
	v_lshlrev_b32_e32 v148, 16, v28
	v_and_b32_e32 v149, 0xffff0000, v28
	v_lshlrev_b32_e32 v150, 16, v29
	v_and_b32_e32 v151, 0xffff0000, v29
	v_lshlrev_b32_e32 v152, 16, v30
	v_and_b32_e32 v153, 0xffff0000, v30
	v_lshlrev_b32_e32 v154, 16, v31
	v_and_b32_e32 v155, 0xffff0000, v31
	global_store_dwordx4 v173, v[148:151], s[100:101]
	global_store_dwordx4 v173, v[152:155], s[100:101] offset:16
	s_add_u32 s98, s98, 0x200000
	s_addc_u32 s99, s99, 0
	s_add_u32 s100, s100, 0x200000
	s_addc_u32 s101, s101, 0
	s_waitcnt vmcnt(39)
	v_lshlrev_b32_e32 v156, 16, v32
	v_and_b32_e32 v157, 0xffff0000, v32
	v_lshlrev_b32_e32 v158, 16, v33
	v_and_b32_e32 v159, 0xffff0000, v33
	v_lshlrev_b32_e32 v160, 16, v34
	v_and_b32_e32 v161, 0xffff0000, v34
	v_lshlrev_b32_e32 v162, 16, v35
	v_and_b32_e32 v163, 0xffff0000, v35
	global_store_dwordx4 v173, v[156:159], s[98:99]
	global_store_dwordx4 v173, v[160:163], s[98:99] offset:16
	s_waitcnt vmcnt(40)
	v_lshlrev_b32_e32 v164, 16, v36
	v_and_b32_e32 v165, 0xffff0000, v36
	v_lshlrev_b32_e32 v166, 16, v37
	v_and_b32_e32 v167, 0xffff0000, v37
	v_lshlrev_b32_e32 v168, 16, v38
	v_and_b32_e32 v169, 0xffff0000, v38
	v_lshlrev_b32_e32 v170, 16, v39
	v_and_b32_e32 v171, 0xffff0000, v39
	global_store_dwordx4 v173, v[164:167], s[100:101]
	global_store_dwordx4 v173, v[168:171], s[100:101] offset:16
	s_add_u32 s98, s98, 0x200000
	s_addc_u32 s99, s99, 0
	s_add_u32 s100, s100, 0x200000
	s_addc_u32 s101, s101, 0
	s_waitcnt vmcnt(40)
	v_lshlrev_b32_e32 v140, 16, v40
	v_and_b32_e32 v141, 0xffff0000, v40
	v_lshlrev_b32_e32 v142, 16, v41
	v_and_b32_e32 v143, 0xffff0000, v41
	v_lshlrev_b32_e32 v144, 16, v42
	v_and_b32_e32 v145, 0xffff0000, v42
	v_lshlrev_b32_e32 v146, 16, v43
	v_and_b32_e32 v147, 0xffff0000, v43
	global_store_dwordx4 v173, v[140:143], s[98:99]
	global_store_dwordx4 v173, v[144:147], s[98:99] offset:16
	s_waitcnt vmcnt(40)
	v_lshlrev_b32_e32 v148, 16, v44
	v_and_b32_e32 v149, 0xffff0000, v44
	v_lshlrev_b32_e32 v150, 16, v45
	v_and_b32_e32 v151, 0xffff0000, v45
	v_lshlrev_b32_e32 v152, 16, v46
	v_and_b32_e32 v153, 0xffff0000, v46
	v_lshlrev_b32_e32 v154, 16, v47
	v_and_b32_e32 v155, 0xffff0000, v47
	global_store_dwordx4 v173, v[148:151], s[100:101]
	global_store_dwordx4 v173, v[152:155], s[100:101] offset:16
	s_add_u32 s98, s98, 0x200000
	s_addc_u32 s99, s99, 0
	s_add_u32 s100, s100, 0x200000
	s_addc_u32 s101, s101, 0
	s_waitcnt vmcnt(40)
	v_lshlrev_b32_e32 v156, 16, v48
	v_and_b32_e32 v157, 0xffff0000, v48
	v_lshlrev_b32_e32 v158, 16, v49
	v_and_b32_e32 v159, 0xffff0000, v49
	v_lshlrev_b32_e32 v160, 16, v50
	v_and_b32_e32 v161, 0xffff0000, v50
	v_lshlrev_b32_e32 v162, 16, v51
	v_and_b32_e32 v163, 0xffff0000, v51
	global_store_dwordx4 v173, v[156:159], s[98:99]
	global_store_dwordx4 v173, v[160:163], s[98:99] offset:16
	s_waitcnt vmcnt(40)
	v_lshlrev_b32_e32 v164, 16, v52
	v_and_b32_e32 v165, 0xffff0000, v52
	v_lshlrev_b32_e32 v166, 16, v53
	v_and_b32_e32 v167, 0xffff0000, v53
	v_lshlrev_b32_e32 v168, 16, v54
	v_and_b32_e32 v169, 0xffff0000, v54
	v_lshlrev_b32_e32 v170, 16, v55
	v_and_b32_e32 v171, 0xffff0000, v55
	global_store_dwordx4 v173, v[164:167], s[100:101]
	global_store_dwordx4 v173, v[168:171], s[100:101] offset:16
	s_add_u32 s98, s98, 0x200000
	s_addc_u32 s99, s99, 0
	s_add_u32 s100, s100, 0x200000
	s_addc_u32 s101, s101, 0
	s_waitcnt vmcnt(40)
	v_lshlrev_b32_e32 v140, 16, v56
	v_and_b32_e32 v141, 0xffff0000, v56
	v_lshlrev_b32_e32 v142, 16, v57
	v_and_b32_e32 v143, 0xffff0000, v57
	v_lshlrev_b32_e32 v144, 16, v58
	v_and_b32_e32 v145, 0xffff0000, v58
	v_lshlrev_b32_e32 v146, 16, v59
	v_and_b32_e32 v147, 0xffff0000, v59
	global_store_dwordx4 v173, v[140:143], s[98:99]
	global_store_dwordx4 v173, v[144:147], s[98:99] offset:16
	s_waitcnt vmcnt(40)
	v_lshlrev_b32_e32 v148, 16, v60
	v_and_b32_e32 v149, 0xffff0000, v60
	v_lshlrev_b32_e32 v150, 16, v61
	v_and_b32_e32 v151, 0xffff0000, v61
	v_lshlrev_b32_e32 v152, 16, v62
	v_and_b32_e32 v153, 0xffff0000, v62
	v_lshlrev_b32_e32 v154, 16, v63
	v_and_b32_e32 v155, 0xffff0000, v63
	global_store_dwordx4 v173, v[148:151], s[100:101]
	global_store_dwordx4 v173, v[152:155], s[100:101] offset:16
	s_add_u32 s98, s98, 0x200000
	s_addc_u32 s99, s99, 0
	s_add_u32 s100, s100, 0x200000
	s_addc_u32 s101, s101, 0
	s_waitcnt vmcnt(40)
	v_lshlrev_b32_e32 v156, 16, v68
	v_and_b32_e32 v157, 0xffff0000, v68
	v_lshlrev_b32_e32 v158, 16, v69
	v_and_b32_e32 v159, 0xffff0000, v69
	v_lshlrev_b32_e32 v160, 16, v70
	v_and_b32_e32 v161, 0xffff0000, v70
	v_lshlrev_b32_e32 v162, 16, v71
	v_and_b32_e32 v163, 0xffff0000, v71
	global_store_dwordx4 v173, v[156:159], s[98:99]
	global_store_dwordx4 v173, v[160:163], s[98:99] offset:16
	s_waitcnt vmcnt(40)
	v_lshlrev_b32_e32 v164, 16, v72
	v_and_b32_e32 v165, 0xffff0000, v72
	v_lshlrev_b32_e32 v166, 16, v73
	v_and_b32_e32 v167, 0xffff0000, v73
	v_lshlrev_b32_e32 v168, 16, v74
	v_and_b32_e32 v169, 0xffff0000, v74
	v_lshlrev_b32_e32 v170, 16, v75
	v_and_b32_e32 v171, 0xffff0000, v75
	global_store_dwordx4 v173, v[164:167], s[100:101]
	global_store_dwordx4 v173, v[168:171], s[100:101] offset:16
	s_add_u32 s98, s98, 0x200000
	s_addc_u32 s99, s99, 0
	s_add_u32 s100, s100, 0x200000
	s_addc_u32 s101, s101, 0
	s_waitcnt vmcnt(40)
	v_lshlrev_b32_e32 v140, 16, v76
	v_and_b32_e32 v141, 0xffff0000, v76
	v_lshlrev_b32_e32 v142, 16, v77
	v_and_b32_e32 v143, 0xffff0000, v77
	v_lshlrev_b32_e32 v144, 16, v78
	v_and_b32_e32 v145, 0xffff0000, v78
	v_lshlrev_b32_e32 v146, 16, v79
	v_and_b32_e32 v147, 0xffff0000, v79
	global_store_dwordx4 v173, v[140:143], s[98:99]
	global_store_dwordx4 v173, v[144:147], s[98:99] offset:16
	s_waitcnt vmcnt(40)
	v_lshlrev_b32_e32 v148, 16, v80
	v_and_b32_e32 v149, 0xffff0000, v80
	v_lshlrev_b32_e32 v150, 16, v81
	v_and_b32_e32 v151, 0xffff0000, v81
	v_lshlrev_b32_e32 v152, 16, v82
	v_and_b32_e32 v153, 0xffff0000, v82
	v_lshlrev_b32_e32 v154, 16, v83
	v_and_b32_e32 v155, 0xffff0000, v83
	global_store_dwordx4 v173, v[148:151], s[100:101]
	global_store_dwordx4 v173, v[152:155], s[100:101] offset:16
	s_add_u32 s98, s98, 0x200000
	s_addc_u32 s99, s99, 0
	s_add_u32 s100, s100, 0x200000
	s_addc_u32 s101, s101, 0
	s_waitcnt vmcnt(40)
	v_lshlrev_b32_e32 v156, 16, v84
	v_and_b32_e32 v157, 0xffff0000, v84
	v_lshlrev_b32_e32 v158, 16, v85
	v_and_b32_e32 v159, 0xffff0000, v85
	v_lshlrev_b32_e32 v160, 16, v86
	v_and_b32_e32 v161, 0xffff0000, v86
	v_lshlrev_b32_e32 v162, 16, v87
	v_and_b32_e32 v163, 0xffff0000, v87
	global_store_dwordx4 v173, v[156:159], s[98:99]
	global_store_dwordx4 v173, v[160:163], s[98:99] offset:16
	s_waitcnt vmcnt(40)
	v_lshlrev_b32_e32 v164, 16, v88
	v_and_b32_e32 v165, 0xffff0000, v88
	v_lshlrev_b32_e32 v166, 16, v89
	v_and_b32_e32 v167, 0xffff0000, v89
	v_lshlrev_b32_e32 v168, 16, v90
	v_and_b32_e32 v169, 0xffff0000, v90
	v_lshlrev_b32_e32 v170, 16, v91
	v_and_b32_e32 v171, 0xffff0000, v91
	global_store_dwordx4 v173, v[164:167], s[100:101]
	global_store_dwordx4 v173, v[168:171], s[100:101] offset:16
	s_add_u32 s98, s98, 0x200000
	s_addc_u32 s99, s99, 0
	s_add_u32 s100, s100, 0x200000
	s_addc_u32 s101, s101, 0
	s_waitcnt vmcnt(40)
	v_lshlrev_b32_e32 v140, 16, v92
	v_and_b32_e32 v141, 0xffff0000, v92
	v_lshlrev_b32_e32 v142, 16, v93
	v_and_b32_e32 v143, 0xffff0000, v93
	v_lshlrev_b32_e32 v144, 16, v94
	v_and_b32_e32 v145, 0xffff0000, v94
	v_lshlrev_b32_e32 v146, 16, v95
	v_and_b32_e32 v147, 0xffff0000, v95
	global_store_dwordx4 v173, v[140:143], s[98:99]
	global_store_dwordx4 v173, v[144:147], s[98:99] offset:16
	s_waitcnt vmcnt(40)
	v_lshlrev_b32_e32 v148, 16, v96
	v_and_b32_e32 v149, 0xffff0000, v96
	v_lshlrev_b32_e32 v150, 16, v97
	v_and_b32_e32 v151, 0xffff0000, v97
	v_lshlrev_b32_e32 v152, 16, v98
	v_and_b32_e32 v153, 0xffff0000, v98
	v_lshlrev_b32_e32 v154, 16, v99
	v_and_b32_e32 v155, 0xffff0000, v99
	global_store_dwordx4 v173, v[148:151], s[100:101]
	global_store_dwordx4 v173, v[152:155], s[100:101] offset:16
	s_add_u32 s98, s98, 0x200000
	s_addc_u32 s99, s99, 0
	s_add_u32 s100, s100, 0x200000
	s_addc_u32 s101, s101, 0
	s_waitcnt vmcnt(40)
	v_lshlrev_b32_e32 v156, 16, v100
	v_and_b32_e32 v157, 0xffff0000, v100
	v_lshlrev_b32_e32 v158, 16, v101
	v_and_b32_e32 v159, 0xffff0000, v101
	v_lshlrev_b32_e32 v160, 16, v102
	v_and_b32_e32 v161, 0xffff0000, v102
	v_lshlrev_b32_e32 v162, 16, v103
	v_and_b32_e32 v163, 0xffff0000, v103
	global_store_dwordx4 v173, v[156:159], s[98:99]
	global_store_dwordx4 v173, v[160:163], s[98:99] offset:16
	s_waitcnt vmcnt(40)
	v_lshlrev_b32_e32 v164, 16, v104
	v_and_b32_e32 v165, 0xffff0000, v104
	v_lshlrev_b32_e32 v166, 16, v105
	v_and_b32_e32 v167, 0xffff0000, v105
	v_lshlrev_b32_e32 v168, 16, v106
	v_and_b32_e32 v169, 0xffff0000, v106
	v_lshlrev_b32_e32 v170, 16, v107
	v_and_b32_e32 v171, 0xffff0000, v107
	global_store_dwordx4 v173, v[164:167], s[100:101]
	global_store_dwordx4 v173, v[168:171], s[100:101] offset:16
	s_add_u32 s98, s98, 0x200000
	s_addc_u32 s99, s99, 0
	s_add_u32 s100, s100, 0x200000
	s_addc_u32 s101, s101, 0
	s_waitcnt vmcnt(40)
	v_lshlrev_b32_e32 v140, 16, v108
	v_and_b32_e32 v141, 0xffff0000, v108
	v_lshlrev_b32_e32 v142, 16, v109
	v_and_b32_e32 v143, 0xffff0000, v109
	v_lshlrev_b32_e32 v144, 16, v110
	v_and_b32_e32 v145, 0xffff0000, v110
	v_lshlrev_b32_e32 v146, 16, v111
	v_and_b32_e32 v147, 0xffff0000, v111
	global_store_dwordx4 v173, v[140:143], s[98:99]
	global_store_dwordx4 v173, v[144:147], s[98:99] offset:16
	s_waitcnt vmcnt(40)
	v_lshlrev_b32_e32 v148, 16, v112
	v_and_b32_e32 v149, 0xffff0000, v112
	v_lshlrev_b32_e32 v150, 16, v113
	v_and_b32_e32 v151, 0xffff0000, v113
	v_lshlrev_b32_e32 v152, 16, v114
	v_and_b32_e32 v153, 0xffff0000, v114
	v_lshlrev_b32_e32 v154, 16, v115
	v_and_b32_e32 v155, 0xffff0000, v115
	global_store_dwordx4 v173, v[148:151], s[100:101]
	global_store_dwordx4 v173, v[152:155], s[100:101] offset:16
	s_add_u32 s98, s98, 0x200000
	s_addc_u32 s99, s99, 0
	s_add_u32 s100, s100, 0x200000
	s_addc_u32 s101, s101, 0
	s_waitcnt vmcnt(40)
	v_lshlrev_b32_e32 v156, 16, v116
	v_and_b32_e32 v157, 0xffff0000, v116
	v_lshlrev_b32_e32 v158, 16, v117
	v_and_b32_e32 v159, 0xffff0000, v117
	v_lshlrev_b32_e32 v160, 16, v118
	v_and_b32_e32 v161, 0xffff0000, v118
	v_lshlrev_b32_e32 v162, 16, v119
	v_and_b32_e32 v163, 0xffff0000, v119
	global_store_dwordx4 v173, v[156:159], s[98:99]
	global_store_dwordx4 v173, v[160:163], s[98:99] offset:16
	s_waitcnt vmcnt(40)
	v_lshlrev_b32_e32 v164, 16, v120
	v_and_b32_e32 v165, 0xffff0000, v120
	v_lshlrev_b32_e32 v166, 16, v121
	v_and_b32_e32 v167, 0xffff0000, v121
	v_lshlrev_b32_e32 v168, 16, v122
	v_and_b32_e32 v169, 0xffff0000, v122
	v_lshlrev_b32_e32 v170, 16, v123
	v_and_b32_e32 v171, 0xffff0000, v123
	global_store_dwordx4 v173, v[164:167], s[100:101]
	global_store_dwordx4 v173, v[168:171], s[100:101] offset:16
	s_add_u32 s98, s98, 0x200000
	s_addc_u32 s99, s99, 0
	s_add_u32 s100, s100, 0x200000
	s_addc_u32 s101, s101, 0
	s_waitcnt vmcnt(40)
	v_lshlrev_b32_e32 v140, 16, v124
	v_and_b32_e32 v141, 0xffff0000, v124
	v_lshlrev_b32_e32 v142, 16, v125
	v_and_b32_e32 v143, 0xffff0000, v125
	v_lshlrev_b32_e32 v144, 16, v126
	v_and_b32_e32 v145, 0xffff0000, v126
	v_lshlrev_b32_e32 v146, 16, v127
	v_and_b32_e32 v147, 0xffff0000, v127
	global_store_dwordx4 v173, v[140:143], s[98:99]
	global_store_dwordx4 v173, v[144:147], s[98:99] offset:16
	s_waitcnt vmcnt(40)
	v_lshlrev_b32_e32 v148, 16, v128
	v_and_b32_e32 v149, 0xffff0000, v128
	v_lshlrev_b32_e32 v150, 16, v129
	v_and_b32_e32 v151, 0xffff0000, v129
	v_lshlrev_b32_e32 v152, 16, v130
	v_and_b32_e32 v153, 0xffff0000, v130
	v_lshlrev_b32_e32 v154, 16, v131
	v_and_b32_e32 v155, 0xffff0000, v131
	global_store_dwordx4 v173, v[148:151], s[100:101]
	global_store_dwordx4 v173, v[152:155], s[100:101] offset:16

.Lxa_unit:
	s_lshr_b32 s20, s18, 21
	s_lshl_b32 s21, s18, 11
	s_add_u32 s21, s21, s13
	s_addc_u32 s20, s20, 0
	s_add_u32 s50, s38, s21
	s_addc_u32 s51, s39, s20
	s_add_u32 s52, s50, 0x1bf00000
	s_addc_u32 s53, s51, 0
	s_add_u32 s50, s50, 0x11f00000
	s_addc_u32 s51, s51, 0
	s_lshl_b32 s21, s19, 11
	s_add_u32 s21, s21, s13
	s_add_u32 s54, s38, s21
	s_addc_u32 s55, s39, 0
	s_add_u32 s56, s54, 0x8600000
	s_addc_u32 s57, s55, 0
	s_add_u32 s54, s54, 0x6e00000
	s_addc_u32 s55, s55, 0
	s_add_u32 s76, s50, 0x80000
	s_addc_u32 s77, s51, 0
	s_add_u32 s72, s54, 0x8000
	s_addc_u32 s73, s55, 0
	global_load_dwordx4 v[234:237], v194, s[54:55]
	global_load_dwordx4 v[238:241], v194, s[72:73]
	s_add_u32 s70, s54, 0x10000
	s_addc_u32 s71, s55, 0
	s_add_u32 s72, s54, 0x18000
	s_addc_u32 s73, s55, 0
	global_load_dwordx4 v[242:245], v194, s[70:71]
	global_load_dwordx4 v[246:249], v194, s[72:73]
	global_load_dwordx4 v[0:3], v195, s[50:51]
	global_load_dwordx4 v[4:7], v195, s[50:51] offset:32
	global_load_dwordx4 v[8:11], v195, s[50:51] offset:64
	global_load_dwordx4 v[12:15], v195, s[50:51] offset:96
	global_load_dwordx4 v[16:19], v195, s[50:51] offset:128
	global_load_dwordx4 v[20:23], v195, s[50:51] offset:160
	global_load_dwordx4 v[24:27], v195, s[50:51] offset:192
	global_load_dwordx4 v[28:31], v195, s[50:51] offset:224
	global_load_dwordx4 v[32:35], v195, s[50:51] offset:256
	global_load_dwordx4 v[36:39], v195, s[50:51] offset:288
	global_load_dwordx4 v[40:43], v195, s[50:51] offset:320
	global_load_dwordx4 v[44:47], v195, s[50:51] offset:352
	global_load_dwordx4 v[48:51], v195, s[50:51] offset:384
	global_load_dwordx4 v[52:55], v195, s[50:51] offset:416
	global_load_dwordx4 v[56:59], v195, s[50:51] offset:448
	global_load_dwordx4 v[60:63], v195, s[50:51] offset:480
	s_barrier
	global_load_dwordx4 v[64:67], v202, s[56:57]
	global_load_dwordx4 v[68:71], v202, s[56:57] offset:2048
	global_load_dwordx4 v[72:75], v202, s[56:57] offset:64
	global_load_dwordx4 v[76:79], v202, s[56:57] offset:2112
	global_load_dwordx4 v[80:83], v202, s[56:57] offset:128
	global_load_dwordx4 v[84:87], v202, s[56:57] offset:2176
	global_load_dwordx4 v[88:91], v202, s[56:57] offset:192
	global_load_dwordx4 v[92:95], v202, s[56:57] offset:2240
	global_load_dwordx4 v[96:99], v202, s[56:57] offset:256
	global_load_dwordx4 v[100:103], v202, s[56:57] offset:2304
	global_load_dwordx4 v[104:107], v202, s[56:57] offset:320
	global_load_dwordx4 v[108:111], v202, s[56:57] offset:2368
	global_load_dwordx4 v[112:115], v202, s[56:57] offset:384
	global_load_dwordx4 v[116:119], v202, s[56:57] offset:2432
	global_load_dwordx4 v[120:123], v202, s[56:57] offset:448
	global_load_dwordx4 v[124:127], v202, s[56:57] offset:2496
	s_mov_b32 s21, 0xffff0000
	s_waitcnt vmcnt(14)
	v_and_b32_e32 v200, 0xffff, v64
	v_lshl_or_b32 v200, v68, 16, v200
	v_lshrrev_b32_e32 v201, 16, v64
	v_and_or_b32 v201, v68, s21, v201
	ds_write_b32 v203, v200
	ds_write_b32 v203, v201 offset:528
	v_and_b32_e32 v200, 0xffff, v65
	v_lshl_or_b32 v200, v69, 16, v200
	v_lshrrev_b32_e32 v201, 16, v65
	v_and_or_b32 v201, v69, s21, v201
	ds_write_b32 v203, v200 offset:1056
	ds_write_b32 v203, v201 offset:1584
	v_and_b32_e32 v200, 0xffff, v66
	v_lshl_or_b32 v200, v70, 16, v200
	v_lshrrev_b32_e32 v201, 16, v66
	v_and_or_b32 v201, v70, s21, v201
	ds_write_b32 v203, v200 offset:2112
	ds_write_b32 v203, v201 offset:2640
	v_and_b32_e32 v200, 0xffff, v67
	v_lshl_or_b32 v200, v71, 16, v200
	v_lshrrev_b32_e32 v201, 16, v67
	v_and_or_b32 v201, v71, s21, v201
	ds_write_b32 v203, v200 offset:3168
	ds_write_b32 v203, v201 offset:3696
	s_waitcnt lgkmcnt(7)
	s_waitcnt vmcnt(12)
	v_and_b32_e32 v200, 0xffff, v72
	v_lshl_or_b32 v200, v76, 16, v200
	v_lshrrev_b32_e32 v201, 16, v72
	v_and_or_b32 v201, v76, s21, v201
	ds_write_b32 v203, v200 offset:16896
	ds_write_b32 v203, v201 offset:17424
	v_and_b32_e32 v200, 0xffff, v73
	v_lshl_or_b32 v200, v77, 16, v200
	v_lshrrev_b32_e32 v201, 16, v73
	v_and_or_b32 v201, v77, s21, v201
	ds_write_b32 v203, v200 offset:17952
	ds_write_b32 v203, v201 offset:18480
	v_and_b32_e32 v200, 0xffff, v74
	v_lshl_or_b32 v200, v78, 16, v200
	v_lshrrev_b32_e32 v201, 16, v74
	v_and_or_b32 v201, v78, s21, v201
	ds_write_b32 v203, v200 offset:19008
	ds_write_b32 v203, v201 offset:19536
	v_and_b32_e32 v200, 0xffff, v75
	v_lshl_or_b32 v200, v79, 16, v200
	v_lshrrev_b32_e32 v201, 16, v75
	v_and_or_b32 v201, v79, s21, v201
	ds_write_b32 v203, v200 offset:20064
	ds_write_b32 v203, v201 offset:20592
	s_waitcnt lgkmcnt(7)
	s_waitcnt vmcnt(10)
	v_and_b32_e32 v200, 0xffff, v80
	v_lshl_or_b32 v200, v84, 16, v200
	v_lshrrev_b32_e32 v201, 16, v80
	v_and_or_b32 v201, v84, s21, v201
	ds_write_b32 v203, v200 offset:33792
	ds_write_b32 v203, v201 offset:34320
	v_and_b32_e32 v200, 0xffff, v81
	v_lshl_or_b32 v200, v85, 16, v200
	v_lshrrev_b32_e32 v201, 16, v81
	v_and_or_b32 v201, v85, s21, v201
	ds_write_b32 v203, v200 offset:34848
	ds_write_b32 v203, v201 offset:35376
	v_and_b32_e32 v200, 0xffff, v82
	v_lshl_or_b32 v200, v86, 16, v200
	v_lshrrev_b32_e32 v201, 16, v82
	v_and_or_b32 v201, v86, s21, v201
	ds_write_b32 v203, v200 offset:35904
	ds_write_b32 v203, v201 offset:36432
	v_and_b32_e32 v200, 0xffff, v83
	v_lshl_or_b32 v200, v87, 16, v200
	v_lshrrev_b32_e32 v201, 16, v83
	v_and_or_b32 v201, v87, s21, v201
	ds_write_b32 v203, v200 offset:36960
	ds_write_b32 v203, v201 offset:37488
	s_waitcnt lgkmcnt(7)
	s_waitcnt vmcnt(8)
	v_and_b32_e32 v200, 0xffff, v88
	v_lshl_or_b32 v200, v92, 16, v200
	v_lshrrev_b32_e32 v201, 16, v88
	v_and_or_b32 v201, v92, s21, v201
	ds_write_b32 v203, v200 offset:50688
	ds_write_b32 v203, v201 offset:51216
	v_and_b32_e32 v200, 0xffff, v89
	v_lshl_or_b32 v200, v93, 16, v200
	v_lshrrev_b32_e32 v201, 16, v89
	v_and_or_b32 v201, v93, s21, v201
	ds_write_b32 v203, v200 offset:51744
	ds_write_b32 v203, v201 offset:52272
	v_and_b32_e32 v200, 0xffff, v90
	v_lshl_or_b32 v200, v94, 16, v200
	v_lshrrev_b32_e32 v201, 16, v90
	v_and_or_b32 v201, v94, s21, v201
	ds_write_b32 v203, v200 offset:52800
	ds_write_b32 v203, v201 offset:53328
	v_and_b32_e32 v200, 0xffff, v91
	v_lshl_or_b32 v200, v95, 16, v200
	v_lshrrev_b32_e32 v201, 16, v91
	v_and_or_b32 v201, v95, s21, v201
	ds_write_b32 v203, v200 offset:53856
	ds_write_b32 v203, v201 offset:54384
	s_waitcnt lgkmcnt(7)
	s_waitcnt vmcnt(6)
	v_and_b32_e32 v200, 0xffff, v96
	v_lshl_or_b32 v200, v100, 16, v200
	v_lshrrev_b32_e32 v201, 16, v96
	v_and_or_b32 v201, v100, s21, v201
	ds_write_b32 v204, v200
	ds_write_b32 v204, v201 offset:528
	v_and_b32_e32 v200, 0xffff, v97
	v_lshl_or_b32 v200, v101, 16, v200
	v_lshrrev_b32_e32 v201, 16, v97
	v_and_or_b32 v201, v101, s21, v201
	ds_write_b32 v204, v200 offset:1056
	ds_write_b32 v204, v201 offset:1584
	v_and_b32_e32 v200, 0xffff, v98
	v_lshl_or_b32 v200, v102, 16, v200
	v_lshrrev_b32_e32 v201, 16, v98
	v_and_or_b32 v201, v102, s21, v201
	ds_write_b32 v204, v200 offset:2112
	ds_write_b32 v204, v201 offset:2640
	v_and_b32_e32 v200, 0xffff, v99
	v_lshl_or_b32 v200, v103, 16, v200
	v_lshrrev_b32_e32 v201, 16, v99
	v_and_or_b32 v201, v103, s21, v201
	ds_write_b32 v204, v200 offset:3168
	ds_write_b32 v204, v201 offset:3696
	s_waitcnt lgkmcnt(7)
	s_waitcnt vmcnt(4)
	v_and_b32_e32 v200, 0xffff, v104
	v_lshl_or_b32 v200, v108, 16, v200
	v_lshrrev_b32_e32 v201, 16, v104
	v_and_or_b32 v201, v108, s21, v201
	ds_write_b32 v204, v200 offset:16896
	ds_write_b32 v204, v201 offset:17424
	v_and_b32_e32 v200, 0xffff, v105
	v_lshl_or_b32 v200, v109, 16, v200
	v_lshrrev_b32_e32 v201, 16, v105
	v_and_or_b32 v201, v109, s21, v201
	ds_write_b32 v204, v200 offset:17952
	ds_write_b32 v204, v201 offset:18480
	v_and_b32_e32 v200, 0xffff, v106
	v_lshl_or_b32 v200, v110, 16, v200
	v_lshrrev_b32_e32 v201, 16, v106
	v_and_or_b32 v201, v110, s21, v201
	ds_write_b32 v204, v200 offset:19008
	ds_write_b32 v204, v201 offset:19536
	v_and_b32_e32 v200, 0xffff, v107
	v_lshl_or_b32 v200, v111, 16, v200
	v_lshrrev_b32_e32 v201, 16, v107
	v_and_or_b32 v201, v111, s21, v201
	ds_write_b32 v204, v200 offset:20064
	ds_write_b32 v204, v201 offset:20592
	s_waitcnt lgkmcnt(7)
	s_waitcnt vmcnt(2)
	v_and_b32_e32 v200, 0xffff, v112
	v_lshl_or_b32 v200, v116, 16, v200
	v_lshrrev_b32_e32 v201, 16, v112
	v_and_or_b32 v201, v116, s21, v201
	ds_write_b32 v204, v200 offset:33792
	ds_write_b32 v204, v201 offset:34320
	v_and_b32_e32 v200, 0xffff, v113
	v_lshl_or_b32 v200, v117, 16, v200
	v_lshrrev_b32_e32 v201, 16, v113
	v_and_or_b32 v201, v117, s21, v201
	ds_write_b32 v204, v200 offset:34848
	ds_write_b32 v204, v201 offset:35376
	v_and_b32_e32 v200, 0xffff, v114
	v_lshl_or_b32 v200, v118, 16, v200
	v_lshrrev_b32_e32 v201, 16, v114
	v_and_or_b32 v201, v118, s21, v201
	ds_write_b32 v204, v200 offset:35904
	ds_write_b32 v204, v201 offset:36432
	v_and_b32_e32 v200, 0xffff, v115
	v_lshl_or_b32 v200, v119, 16, v200
	v_lshrrev_b32_e32 v201, 16, v115
	v_and_or_b32 v201, v119, s21, v201
	ds_write_b32 v204, v200 offset:36960
	ds_write_b32 v204, v201 offset:37488
	s_waitcnt lgkmcnt(7)
	s_waitcnt vmcnt(0)
	v_and_b32_e32 v200, 0xffff, v120
	v_lshl_or_b32 v200, v124, 16, v200
	v_lshrrev_b32_e32 v201, 16, v120
	v_and_or_b32 v201, v124, s21, v201
	ds_write_b32 v204, v200 offset:50688
	ds_write_b32 v204, v201 offset:51216
	v_and_b32_e32 v200, 0xffff, v121
	v_lshl_or_b32 v200, v125, 16, v200
	v_lshrrev_b32_e32 v201, 16, v121
	v_and_or_b32 v201, v125, s21, v201
	ds_write_b32 v204, v200 offset:51744
	ds_write_b32 v204, v201 offset:52272
	v_and_b32_e32 v200, 0xffff, v122
	v_lshl_or_b32 v200, v126, 16, v200
	v_lshrrev_b32_e32 v201, 16, v122
	v_and_or_b32 v201, v126, s21, v201
	ds_write_b32 v204, v200 offset:52800
	ds_write_b32 v204, v201 offset:53328
	v_and_b32_e32 v200, 0xffff, v123
	v_lshl_or_b32 v200, v127, 16, v200
	v_lshrrev_b32_e32 v201, 16, v123
	v_and_or_b32 v201, v127, s21, v201
	ds_write_b32 v204, v200 offset:53856
	ds_write_b32 v204, v201 offset:54384
	s_waitcnt lgkmcnt(7)
	s_waitcnt vmcnt(0) lgkmcnt(0)
	s_barrier
